# scan workgroups on XCDs 0-3 and attention workgroups on XCDs 4-7 (role by blockIdx bit 2), both workgroups of a (batch, head) pair on one XCD
# baseline (speedup 1.0000x reference)
; __device__ __forceinline__ int otid() { int t = threadIdx.x; asm volatile("" : "+v"(t)); return t; }
; __device__ __forceinline__ int obid() { int b = blockIdx.x; asm volatile("" : "+s"(b)); return b; }
; __device__ __forceinline__ void phase_scan2(const Params& p, int l, LAS unsigned char* lds) {
;     ...
;     const int tid = otid(), wid = tid >> 6, lane = tid & 63, fr = lane & 15, fq = lane >> 4;
;     constexpr int NCH = SEQ / 16, NRD = (NCH + SC_NP - 1) / SC_NP;
;     for (int job = obid(); job < 256; job += gridDim.x) {
;         const int bh = job >> 2, rg = job & 3, b = bh >> 3, h = bh & 7;
;         const size_t tok0 = (size_t)b * SEQ;
;         const int pw = wid - 3, j = lane;
.Lsc_entry:
	v_lshrrev_b32_e32 v4, 6, v183
	s_add_u32 s26, s74, 0xc000000
	s_addc_u32 s27, s75, 0
	v_and_b32_e32 v1, 15, v183
	v_readfirstlane_b32 s25, v4
	s_add_u32 s36, s74, 0x13000000
	s_addc_u32 s37, s75, 0
	v_bfe_u32 v2, v183, 4, 2
	v_lshrrev_b32_e32 v4, 2, v1
	v_and_b32_e32 v7, 3, v1
	s_add_u32 s38, s74, 0xa000000
	s_addc_u32 s39, s75, 0
	v_lshlrev_b32_e32 v6, 5, v1
	v_lshl_add_u32 v4, v2, 2, v4
	v_lshlrev_b32_e32 v7, 3, v7
	s_add_u32 s46, s74, 0x11000000
	s_mov_b32 s13, s5
	s_addc_u32 s47, s75, 0
	v_and_b32_e32 v0, 63, v183
	v_lshl_add_u32 v6, v2, 3, v6
	v_lshl_add_u32 v7, v4, 5, v7
	s_and_b32 s0, s13, 4
	s_cmp_lg_u32 s0, 0
	s_cbranch_scc1 .Lsc_exit
.Lsc_job:
	s_lshr_b32 s0, s13, 4
	s_lshl_b32 s0, s0, 2
	s_and_b32 s53, s13, 3
	s_add_u32 s0, s0, s53
	s_bfe_u32 s53, s13, 0x10003
	s_lshl_b32 s53, s53, 1
	s_lshr_b32 s54, s0, 3
	s_and_b32 s52, s0, 7
	s_cmp_eq_u32 s25, 0
	s_cbranch_scc1 .Lsc_consumer
	s_cmp_eq_u32 s25, 4
	s_cbranch_scc1 .Lsc_consumer

; #define LAS __attribute__((address_space(3)))
; __device__ __forceinline__ int otid() { int t = threadIdx.x; asm volatile("" : "+v"(t)); return t; }
; __device__ __forceinline__ int obid() { int b = blockIdx.x; asm volatile("" : "+s"(b)); return b; }
; __device__ __forceinline__ void phase_attn(const Params& p, int l, LAS unsigned char* ldsb) {
;     ...
;     const int tid = otid(), wid = tid >> 6, lane = tid & 63, fr = lane & 15, fq = lane >> 4;
;     LAS bf16_t* Ks = (LAS bf16_t*)ldsb;
;     LAS bf16_t* Vt = (LAS bf16_t*)(ldsb + 36864);
;     LAS float* biasL = (LAS float*)(ldsb + 70656);
;     LAS bf16_t* Pw = (LAS bf16_t*)(ldsb + 72704) + wid * (16 * 168);
;     for (int item = obid(); item < 512; item += gridDim.x) {
;         const int g = item & 1, n = (item >> 1) & 31, b = item >> 6;
;         const long tokc = (long)b * SEQ + n * 128, tokp = tokc - 128;
;         for (int idx = tid; idx < 2048; idx += 512) {
;             const int key = idx >> 3, d8 = idx & 7; u32x4 v = (u32x4){0u, 0u, 0u, 0u}, kv = (u32x4){0u, 0u, 0u, 0u};
;             if (n > 0 || key >= 128) { const bf16_t* src = QKV + (size_t)(tokp + key) * 768 + 512 + g * 64 + d8 * 8; kv = *(const u32x4*)src; v = *(const u32x4*)(src + 128); }
;             *(LAS u32x4*)(Ks + key * 72 + d8 * 8) = kv;
; #pragma unroll
;             for (int e = 0; e < 8; ++e) Vt[(d8 * 8 + e) * 264 + key] = (bf16_t)((e & 1) ? (v[e >> 1] >> 16) : (v[e >> 1] & 0xffffu));
;         }
;         { const int hl = tid >> 7, d = tid & 127; int bk = d;
;           if (d >= 16) { bk = 16 + (int)(__logf((float)d * 0.0625f) * (16.f / 2.07944154168f)); bk = bk > 31 ? 31 : bk; }
;           biasL[tid] = relb[bk * 8 + g * 4 + hl]; }
;         __syncthreads();
;         const int hl = wid >> 1, hq = g * 4 + hl; const float sink = sinks[hq];
.Lat_entry:
	s_and_b32 s25, s5, 4
	s_cmp_eq_u32 s25, 0
	s_cbranch_scc1 .Lat_end
	v_and_b32_e32 v0, 63, v183
	v_and_b32_e32 v1, 15, v183
	v_bfe_u32 v2, v183, 4, 2
	v_lshrrev_b32_e32 v4, 6, v183
	s_nop 0
	v_readfirstlane_b32 s44, v4
	s_nop 0
	s_lshr_b32 s45, s44, 1
	s_and_b32 s46, s44, 1
	v_readlane_b32 s0, v252, 0
	v_readlane_b32 s1, v252, 1
	s_sub_u32 s0, s0, 0xe0
	s_subb_u32 s1, s1, 0
	s_load_dwordx2 s[14:15], s[0:1], 0x38
	s_load_dwordx2 s[26:27], s[0:1], 0x40
	v_readlane_b32 s85, v243, 45
	s_nop 0
	s_lshr_b32 s85, s85, 1
	s_mov_b32 s82, 0x3e38aa3b
	v_lshrrev_b32_e32 v4, 3, v183
	v_and_b32_e32 v5, 7, v183
	v_mul_u32_u24_e32 v7, 1536, v4
	v_lshl_add_u32 v7, v5, 4, v7
	v_and_b32_e32 v6, 7, v4
	v_xor_b32_e32 v6, v6, v5
	v_lshlrev_b32_e32 v6, 4, v6
	v_lshl_add_u32 v6, v4, 7, v6
	v_bfe_u32 v3, v4, 1, 3
	v_xor_b32_e32 v3, v3, v5
	v_lshlrev_b32_e32 v3, 4, v3
	v_lshl_add_u32 v3, v4, 7, v3
	v_and_b32_e32 v8, 127, v183
	v_lshrrev_b32_e32 v4, 7, v183
	v_cvt_f32_u32_e32 v5, v8
	v_mul_f32_e32 v5, 0x3d800000, v5
	v_max_f32_e32 v5, 1.0, v5
	v_log_f32_e32 v5, v5
	s_nop 0
	v_mul_f32_e32 v5, 0x40aaaaab, v5
	v_cvt_i32_f32_e32 v5, v5
	v_add_u32_e32 v5, 16, v5
	v_min_u32_e32 v5, 31, v5
	v_cmp_gt_u32_e32 vcc, 16, v8
	s_nop 1
	v_cndmask_b32_e32 v10, v5, v8, vcc
	v_lshlrev_b32_e32 v10, 5, v10
	v_lshl_add_u32 v10, v4, 2, v10
	v_mul_u32_u24_e32 v9, 3328, v4
	v_sub_u32_e32 v5, 160, v8
	v_lshl_add_u32 v9, v5, 2, v9
	v_add_u32_e32 v9, 131072, v9
	v_add_u32_e32 v5, 96, v8
	v_subrev_u32_e32 v29, 32, v8
	v_cmp_gt_u32_e32 vcc, 32, v8
	s_nop 1
	v_cndmask_b32_e32 v5, v5, v29, vcc
	v_sub_u32_e32 v5, 160, v5
	v_mul_u32_u24_e32 v11, 3328, v4
	v_lshl_add_u32 v11, v5, 2, v11
	v_add_u32_e32 v11, 131072, v11
	v_lshlrev_b32_e32 v5, 2, v183
	v_add_u32_e32 v5, 144384, v5
	v_cmp_gt_u32_e32 vcc, 65, v8
	s_nop 1
	v_cndmask_b32_e32 v11, v5, v11, vcc
	v_bfe_u32 v4, v1, 1, 3
	v_xor_b32_e32 v4, v4, v2
	v_lshlrev_b32_e32 v4, 4, v4
	v_lshl_add_u32 v13, v1, 7, v4
	v_xor_b32_e32 v14, 64, v13
	v_and_b32_e32 v4, 3, v1
	v_mul_u32_u24_e32 v17, 832, v4
	v_and_b32_e32 v4, 12, v1
	v_lshlrev_b32_e32 v4, 2, v4
	v_sub_u32_e32 v17, v17, v4
	v_lshl_add_u32 v17, v2, 4, v17
	s_mul_i32 s51, s45, 3328
	s_add_u32 s51, s51, 131072
	v_add_u32_e32 v17, s51, v17
	v_lshrrev_b32_e32 v4, 2, v1
	v_lshl_add_u32 v4, v2, 2, v4
	v_and_b32_e32 v5, 7, v4
	v_bfe_u32 v29, v1, 1, 1
	v_and_b32_e32 v30, 1, v1
	v_lshlrev_b32_e32 v30, 3, v30
	v_lshl_add_u32 v30, v4, 7, v30
	v_add_u32_e32 v30, 32768, v30
	v_or_b32_e32 v4, 0, v29
	v_xor_b32_e32 v4, v4, v5
	v_lshl_add_u32 v19, v4, 4, v30
	v_or_b32_e32 v4, 2, v29
	v_xor_b32_e32 v4, v4, v5
	v_lshl_add_u32 v20, v4, 4, v30
	v_or_b32_e32 v4, 4, v29
	v_xor_b32_e32 v4, v4, v5
	v_lshl_add_u32 v21, v4, 4, v30
	v_or_b32_e32 v4, 6, v29
	v_xor_b32_e32 v4, v4, v5
	v_lshl_add_u32 v22, v4, 4, v30
	v_mul_u32_u24_e32 v27, 1536, v1
	v_lshl_add_u32 v27, v2, 4, v27
	v_lshlrev_b32_e32 v28, 10, v1
	v_lshl_add_u32 v28, v2, 3, v28
	v_xor_b32_e32 v29, 16, v0
	v_lshlrev_b32_e32 v29, 2, v29
	v_xor_b32_e32 v30, 32, v0
	v_lshlrev_b32_e32 v30, 2, v30
	s_lshr_b32 s25, s5, 3
	s_lshl_b32 s25, s25, 2
	s_and_b32 s2, s5, 3
	s_add_u32 s25, s25, s2
	s_and_b32 s2, s25, 1
	s_lshr_b32 s13, s25, 1
	s_and_b32 s13, s13, 31
	s_lshr_b32 s25, s25, 6
	s_lshl_b32 s32, s25, 12
	s_lshl_b32 s51, s13, 7
	s_add_u32 s32, s32, s51
	s_lshl_b32 s47, s2, 2
	s_add_u32 s47, s47, s45
	s_waitcnt lgkmcnt(0)
	s_mov_b32 s87, 0
